# NSA window-branch tiles 0,1 prefetched at selected-loop start into v[240:255]; window prologue moves them instead of loading (no exposed load latency)
# baseline (speedup 1.0000x reference)
.LBB0_1038:
	s_or_b64 exec, exec, s[0:1]
	s_bcnt1_i32_b32 s0, s21
	s_bcnt1_i32_b32 s1, s22
	s_bcnt1_i32_b32 s21, s23
	s_lshl_b32 s22, s40, 25
	s_add_u32 s22, s36, s22
	s_addc_u32 s23, s37, 0
	s_bcnt1_i32_b32 s20, s20
	s_add_i32 s0, s0, s20
	s_add_i32 s79, s0, s1
	s_add_i32 s79, s79, s21
	s_lshl_b32 s0, s29, 7
	s_add_u32 s24, s22, s0
	v_sub_co_u32_e64 v32, s[0:1], s79, 1
	s_waitcnt lgkmcnt(0)
	s_barrier
	s_nop 0
	v_cndmask_b32_e64 v0, 0, -1, s[0:1]
	v_lshlrev_b32_e32 v0, 2, v0
	v_add_u32_e32 v0, s72, v0
	ds_read_b32 v0, v0
	s_addc_u32 s25, s23, 0
	s_lshl_b32 s0, s47, 20
	s_add_u32 s20, s55, s0
	s_addc_u32 s21, s56, 0
	s_waitcnt lgkmcnt(0)
	v_readfirstlane_b32 s0, v0
	s_lshl_b32 s0, s0, 6
	s_ashr_i32 s1, s0, 31
	s_lshl_b64 s[22:23], s[0:1], 12
	s_add_u32 s22, s24, s22
	s_addc_u32 s23, s25, s23
	s_lshl_b64 s[0:1], s[0:1], 1
	s_add_u32 s0, s20, s0
	s_addc_u32 s1, s21, s1
	s_cmp_lt_u32 s79, 2
	v_mov_b32_e32 v139, v123
	v_mov_b32_e32 v141, v123
	s_cselect_b64 vcc, -1, 0
	v_lshl_add_u64 v[0:1], s[22:23], 0, v[138:139]
	v_lshl_add_u64 v[2:3], s[0:1], 0, v[140:141]
	v_cndmask_b32_e32 v8, 1, v32, vcc
	v_lshl_add_u64 v[0:1], v[0:1], 0, v[122:123]
	v_lshl_add_u64 v[4:5], v[2:3], 0, v[122:123]
	v_lshlrev_b32_e32 v8, 2, v8
	global_load_dwordx4 v[0:3], v[0:1], off offset:2560
	s_nop 0
	global_load_dwordx4 v[4:7], v[4:5], off
	v_add_u32_e32 v8, s72, v8
	ds_read_b32 v8, v8
	v_readfirstlane_b32 s80, v32
	v_add_f32_e32 v137, v146, v146
	v_mul_f32_e32 v188, 0x40400000, v146
	v_mul_f32_e32 v189, 0x41800000, v146
	s_waitcnt lgkmcnt(0)
	v_readfirstlane_b32 s0, v8
	s_lshl_b32 s0, s0, 6
	s_ashr_i32 s1, s0, 31
	s_lshl_b64 s[22:23], s[0:1], 12
	s_add_u32 s22, s24, s22
	s_addc_u32 s23, s25, s23
	s_lshl_b64 s[0:1], s[0:1], 1
	s_add_u32 s0, s20, s0
	s_addc_u32 s1, s21, s1
	v_lshl_add_u64 v[8:9], s[22:23], 0, v[138:139]
	v_lshl_add_u64 v[10:11], s[0:1], 0, v[140:141]
	v_lshl_add_u64 v[8:9], v[8:9], 0, v[122:123]
	v_lshl_add_u64 v[12:13], v[10:11], 0, v[122:123]
	global_load_dwordx4 v[8:11], v[8:9], off offset:2560
	s_nop 0
	global_load_dwordx4 v[12:15], v[12:13], off
	s_cmp_lt_u32 s79, 3
	s_cselect_b64 s[0:1], -1, 0
	v_cndmask_b32_e64 v16, 2, v32, s[0:1]
	v_lshlrev_b32_e32 v16, 2, v16
	v_add_u32_e32 v16, s72, v16
	v_mul_f32_e32 v190, 0x42000000, v146
	v_mul_f32_e32 v191, 0x42400000, v146
	v_mul_f32_e32 v192, 0, v146
	s_waitcnt vmcnt(3)
	ds_write_b128 v151, v[0:3]
	s_waitcnt vmcnt(2)
	ds_write2_b64 v187, v[4:5], v[6:7] offset1:2
	s_waitcnt vmcnt(1)
	ds_write_b128 v151, v[8:11] offset:10240
	s_waitcnt vmcnt(0)
	ds_write2_b64 v186, v[12:13], v[14:15] offset1:2
	ds_read_b32 v0, v16
	s_waitcnt lgkmcnt(0)
	v_readfirstlane_b32 s0, v0
	s_lshl_b32 s0, s0, 6
	s_ashr_i32 s1, s0, 31
	s_lshl_b64 s[22:23], s[0:1], 12
	s_add_u32 s22, s24, s22
	s_addc_u32 s23, s25, s23
	s_lshl_b64 s[0:1], s[0:1], 1
	s_add_u32 s0, s20, s0
	s_addc_u32 s1, s21, s1
	s_cmp_lt_u32 s79, 4
	v_lshl_add_u64 v[0:1], s[22:23], 0, v[138:139]
	v_lshl_add_u64 v[2:3], s[0:1], 0, v[140:141]
	s_cselect_b64 s[0:1], -1, 0
	v_lshl_add_u64 v[0:1], v[0:1], 0, v[122:123]
	v_cndmask_b32_e64 v4, 3, v32, s[0:1]
	v_lshl_add_u64 v[2:3], v[2:3], 0, v[122:123]
	global_load_dwordx4 v[20:23], v[0:1], off offset:2560
	global_load_dwordx4 v[16:19], v[2:3], off
	v_lshlrev_b32_e32 v0, 2, v4
	v_add_u32_e32 v0, s72, v0
	ds_read_b32 v0, v0
	s_waitcnt lgkmcnt(0)
	v_readfirstlane_b32 s0, v0
	s_lshl_b32 s0, s0, 6
	s_ashr_i32 s1, s0, 31
	s_lshl_b64 s[22:23], s[0:1], 12
	s_add_u32 s22, s24, s22
	s_addc_u32 s23, s25, s23
	s_lshl_b64 s[0:1], s[0:1], 1
	s_add_u32 s0, s20, s0
	v_lshl_add_u64 v[0:1], s[22:23], 0, v[138:139]
	s_addc_u32 s1, s21, s1
	v_lshl_add_u64 v[0:1], v[0:1], 0, v[122:123]
	v_lshl_add_u64 v[2:3], s[0:1], 0, v[140:141]
	v_lshl_add_u64 v[2:3], v[2:3], 0, v[122:123]
	global_load_dwordx4 v[28:31], v[0:1], off offset:2560
	global_load_dwordx4 v[24:27], v[2:3], off
	s_waitcnt lgkmcnt(0)
	s_barrier
	s_lshl_b32 s98, s47, 20
	s_add_u32 s98, s57, s98
	s_addc_u32 s99, s60, 0
	s_add_i32 s29, s74, 0xfffffe01
	s_andn2_b32 s29, s29, 63
	s_cmp_gt_i32 s75, 31
	s_cselect_b32 s29, s29, 0
	s_sub_i32 s30, s74, s29
	s_ashr_i32 s30, s30, 6
	v_mov_b32_e32 v4, v138
	v_mov_b32_e32 v5, 0
	v_mov_b32_e32 v6, v140
	v_mov_b32_e32 v7, 0
	s_min_i32 s22, s30, 0
	s_lshl_b32 s22, s22, 6
	s_add_i32 s22, s22, s29
	s_ashr_i32 s23, s22, 31
	s_lshl_b64 s[100:101], s[22:23], 12
	s_add_u32 s100, s24, s100
	s_addc_u32 s101, s25, s101
	s_lshl_b64 s[22:23], s[22:23], 1
	s_add_u32 s22, s98, s22
	s_addc_u32 s23, s99, s23
	v_lshl_add_u64 v[0:1], s[100:101], 0, v[4:5]
	v_lshl_add_u64 v[2:3], s[22:23], 0, v[6:7]
	v_lshl_add_u64 v[0:1], v[0:1], 0, v[122:123]
	v_lshl_add_u64 v[2:3], v[2:3], 0, v[122:123]
	global_load_dwordx4 v[240:243], v[0:1], off offset:3072
	global_load_dwordx4 v[244:247], v[2:3], off
	s_min_i32 s22, s30, 1
	s_lshl_b32 s22, s22, 6
	s_add_i32 s22, s22, s29
	s_ashr_i32 s23, s22, 31
	s_lshl_b64 s[100:101], s[22:23], 12
	s_add_u32 s100, s24, s100
	s_addc_u32 s101, s25, s101
	s_lshl_b64 s[22:23], s[22:23], 1
	s_add_u32 s22, s98, s22
	s_addc_u32 s23, s99, s23
	v_lshl_add_u64 v[0:1], s[100:101], 0, v[4:5]
	v_lshl_add_u64 v[2:3], s[22:23], 0, v[6:7]
	v_lshl_add_u64 v[0:1], v[0:1], 0, v[122:123]
	v_lshl_add_u64 v[2:3], v[2:3], 0, v[122:123]
	global_load_dwordx4 v[248:251], v[0:1], off offset:3072
	global_load_dwordx4 v[252:255], v[2:3], off
	v_lshl_add_u64 v[0:1], s[24:25], 0, v[138:139]
	v_lshl_add_u64 v[120:121], v[0:1], 0, v[122:123]
	s_and_b64 vcc, exec, vcc
	s_cbranch_vccnz .LBB0_1050
	v_lshl_add_u64 v[0:1], s[20:21], 0, v[140:141]
	v_mov_b32_e32 v36, 0
	v_lshl_add_u64 v[148:149], v[0:1], 0, v[122:123]
	v_sub_u32_e32 v139, v144, v124
	v_mov_b32_e32 v32, v123
	v_mov_b32_e32 v33, v123
	v_mov_b32_e32 v34, v123
	v_mov_b32_e32 v35, v123
	s_mov_b32 s83, 5
	s_movk_i32 s81, 0x80
	s_mov_b32 s82, s72
	v_mov_b32_e32 v37, v36
	v_mov_b32_e32 v38, v36
	v_mov_b32_e32 v39, v36
	v_mov_b32_e32 v40, v36
	v_mov_b32_e32 v41, v36
	v_mov_b32_e32 v42, v36
	v_mov_b32_e32 v43, v36
	v_mov_b32_e32 v44, v36
	v_mov_b32_e32 v45, v36
	v_mov_b32_e32 v46, v36
	v_mov_b32_e32 v47, v36
	v_mov_b32_e32 v84, v36
	v_mov_b32_e32 v85, v36
	v_mov_b32_e32 v86, v36
	v_mov_b32_e32 v87, v36

.LBB0_1059:
	s_lshl_b32 s0, s80, 1
	s_add_u32 s0, s57, s0
	s_addc_u32 s1, s60, 0
	s_add_i32 s20, s74, 0xfffffe01
	s_andn2_b32 s20, s20, 63
	s_cmp_gt_i32 s75, 31
	s_cselect_b32 s20, s20, 0
	s_sub_i32 s21, s74, s20
	s_ashr_i32 s21, s21, 6
	s_min_i32 s22, s21, 0
	s_lshl_b32 s22, s22, 6
	s_add_i32 s22, s22, s20
	s_ashr_i32 s23, s22, 31
	s_lshl_b64 s[26:27], s[22:23], 12
	s_add_u32 s26, s24, s26
	s_addc_u32 s27, s25, s27
	s_lshl_b64 s[22:23], s[22:23], 1
	s_add_u32 s22, s0, s22
	s_addc_u32 s23, s1, s23
	v_mov_b32_e32 v141, v123
	s_waitcnt vmcnt(2)
	v_lshl_add_u64 v[18:19], s[22:23], 0, v[140:141]
	s_min_i32 s22, s21, 1
	s_lshl_b32 s22, s22, 6
	s_add_i32 s22, s22, s20
	v_mov_b32_e32 v139, v123
	s_ashr_i32 s23, s22, 31
	v_lshl_add_u64 v[16:17], s[26:27], 0, v[138:139]
	s_lshl_b64 s[26:27], s[22:23], 12
	s_add_u32 s26, s24, s26
	s_addc_u32 s27, s25, s27
	s_lshl_b64 s[22:23], s[22:23], 1
	s_add_u32 s22, s0, s22
	s_addc_u32 s23, s1, s23
	v_lshl_add_u64 v[16:17], v[16:17], 0, v[122:123]
	v_lshl_add_u64 v[20:21], v[18:19], 0, v[122:123]
	s_waitcnt vmcnt(0)
	v_lshl_add_u64 v[24:25], s[26:27], 0, v[138:139]
	v_lshl_add_u64 v[26:27], s[22:23], 0, v[140:141]
	v_mov_b32_e32 v16, v240
	v_mov_b32_e32 v17, v241
	v_mov_b32_e32 v18, v242
	v_mov_b32_e32 v19, v243
	s_nop 0
	v_mov_b32_e32 v20, v244
	v_mov_b32_e32 v21, v245
	v_mov_b32_e32 v22, v246
	v_mov_b32_e32 v23, v247
	v_lshl_add_u64 v[24:25], v[24:25], 0, v[122:123]
	v_lshl_add_u64 v[28:29], v[26:27], 0, v[122:123]
	v_mov_b32_e32 v24, v248
	v_mov_b32_e32 v25, v249
	v_mov_b32_e32 v26, v250
	v_mov_b32_e32 v27, v251
	s_nop 0
	v_mov_b32_e32 v28, v252
	v_mov_b32_e32 v29, v253
	v_mov_b32_e32 v30, v254
	v_mov_b32_e32 v31, v255
	s_min_i32 s22, s21, 2
	s_lshl_b32 s22, s22, 6
	s_add_i32 s22, s22, s20
	s_ashr_i32 s23, s22, 31
	s_lshl_b64 s[26:27], s[22:23], 12
	s_add_u32 s26, s24, s26
	s_addc_u32 s27, s25, s27
	s_lshl_b64 s[22:23], s[22:23], 1
	s_add_u32 s22, s0, s22
	s_waitcnt lgkmcnt(3)
	v_lshl_add_u64 v[32:33], s[26:27], 0, v[138:139]
	s_addc_u32 s23, s1, s23
	s_min_i32 s26, s21, 3
	v_lshl_add_u64 v[34:35], s[22:23], 0, v[140:141]
	s_lshl_b32 s22, s26, 6
	s_add_i32 s22, s22, s20
	s_ashr_i32 s23, s22, 31
	s_lshl_b64 s[26:27], s[22:23], 12
	s_add_u32 s24, s24, s26
	s_addc_u32 s25, s25, s27
	s_lshl_b64 s[22:23], s[22:23], 1
	s_add_u32 s22, s0, s22
	v_lshl_add_u64 v[32:33], v[32:33], 0, v[122:123]
	v_lshl_add_u64 v[34:35], v[34:35], 0, v[122:123]
	s_addc_u32 s23, s1, s23
	s_waitcnt lgkmcnt(2)
	global_load_dwordx4 v[36:39], v[32:33], off offset:3072
	s_nop 0
	global_load_dwordx4 v[32:35], v[34:35], off
	s_waitcnt lgkmcnt(1)
	v_lshl_add_u64 v[40:41], s[24:25], 0, v[138:139]
	v_lshl_add_u64 v[42:43], s[22:23], 0, v[140:141]
	v_lshl_add_u64 v[40:41], v[40:41], 0, v[122:123]
	v_lshl_add_u64 v[42:43], v[42:43], 0, v[122:123]
	s_mov_b32 s23, 0
	s_cmp_lt_i32 s21, 1
	s_mov_b32 s24, 0
	s_waitcnt vmcnt(5)
	ds_write_b128 v151, v[16:19]
	s_waitcnt vmcnt(4)
	ds_write2_b64 v187, v[20:21], v[22:23] offset1:2
	s_waitcnt vmcnt(3)
	ds_write_b128 v151, v[24:27] offset:10240
	s_waitcnt vmcnt(2)
	ds_write2_b64 v186, v[28:29], v[30:31] offset1:2
	s_waitcnt lgkmcnt(4)
	global_load_dwordx4 v[44:47], v[40:41], off offset:3072
	s_nop 0
	global_load_dwordx4 v[40:43], v[42:43], off
	s_waitcnt lgkmcnt(0)
	s_barrier
	s_cbranch_scc1 .LBB0_1068
	v_lshl_add_u64 v[16:17], s[0:1], 0, v[140:141]
	v_lshl_add_u64 v[106:107], v[16:17], 0, v[122:123]
	v_add_u32_e32 v16, s74, v171
	v_mov_b32_e32 v86, 0
	s_add_i32 s22, s74, 0xfffffe10
	v_subrev_u32_e32 v81, s20, v16
	v_mov_b32_e32 v87, v86
	v_mov_b32_e32 v88, v86
	v_mov_b32_e32 v89, v86
	s_mov_b32 s23, 5
	v_mov_b32_e32 v90, v86
	v_mov_b32_e32 v91, v86
	v_mov_b32_e32 v92, v86
	v_mov_b32_e32 v93, v86
	v_mov_b32_e32 v94, v86
	v_mov_b32_e32 v95, v86
	v_mov_b32_e32 v96, v86
	v_mov_b32_e32 v97, v86
	v_mov_b32_e32 v98, v86
	v_mov_b32_e32 v99, v86
	v_mov_b32_e32 v100, v86
	v_mov_b32_e32 v101, v86
	v_mov_b32_e32 v102, v86
	v_mov_b32_e32 v103, v86
	v_mov_b32_e32 v104, v86
	v_mov_b32_e32 v105, v86
